# P2b too: next unit's Q rows requested at the top of the last tile
# baseline (speedup 1.0000x reference)
; #define GAS __attribute__((address_space(1)))
; __device__ __forceinline__ void at_load_q(bf16x8 (&qr)[8], const bf16_t* qb, int tq0, int dil, int lane) {
;     const bf16_t* qrow = qb + (size_t)(tq0 + dil * (lane & 31)) * 128 + (lane >> 5) * 8;
; #pragma unroll
;     for (int s = 0; s < 8; ++s) qr[s] = *(const GAS bf16x8*)(qrow + 16 * s);
; __device__ __forceinline__ void attn_unit(const bool FINAL, const bool HN, LAS unsigned char* wl, const bf16_t* qb, const bf16_t* kb, const bf16_t* vb, int tq0, int dil, float sl, bf16x8 (&qr)[8], const bf16_t* nqb, const bf16_t* nkb, const bf16_t* nvb, int ntq0, int ndil, ...
;     ...
; #pragma unroll
;         for (int s = 0; s < 8; ++s) p = __builtin_amdgcn_mfma_f32_32x32x16_fp8_fp8(kf[s], q8[s], p, 0, 0, 0);
;         const float relb = (float)(32 * n + 4 * hi - 64 - r32) - 8.0f;
;     ...
;         float tmax = -1e30f;
;         if (interior && n == 2) {
; #pragma unroll
;             for (int r = 0; r < 16; ++r) { const float rel = relb + AT_CR(r); p[r] = p[r] - sl * fabsf(rel); tmax = fmaxf(tmax, p[r]); }
;         } else if (interior) {
;             const float ssl = (n < 2) ? sl : -sl;
;             if (n == 0) {
; #pragma unroll
;                 for (int r = 0; r < 16; ++r) { const float rel = relb + AT_CR(r); const float v = __builtin_fmaf(ssl, rel, p[r]); p[r] = (rel >= -64.f) ? v : -1e30f; tmax = fmaxf(tmax, p[r]); }
;             } else if (n == 4) {
; #pragma unroll
;                 for (int r = 0; r < 16; ++r) { const float rel = relb + AT_CR(r); const float v = __builtin_fmaf(ssl, rel, p[r]); p[r] = (rel <= 64.f) ? v : -1e30f; tmax = fmaxf(tmax, p[r]); }
;             } else {
; #pragma unroll
;                 for (int r = 0; r < 16; ++r) { const float rel = relb + AT_CR(r); p[r] = __builtin_fmaf(ssl, rel, p[r]); tmax = fmaxf(tmax, p[r]); }
;             }
;         } else {
; #pragma unroll
;             for (int r = 0; r < 16; ++r) { const float rel = relb + AT_CR(r); const bool ok = (rel >= lo_i) && (rel <= hi_i);
;                 p[r] = ok ? p[r] - sl * fabsf(rel) : -1e30f; tmax = fmaxf(tmax, p[r]); }
.LBB0_484:
	s_cmpk_lg_i32 s15, 0x80
	s_cbranch_scc1 mk_p2b_q_skip
	s_cmp_lg_u64 s[46:47], 0
	s_cbranch_scc0 mk_p2b_q_skip
	v_or_b32_e32 v68, s14, v200
	v_lshlrev_b32_e32 v68, 8, v68
	v_mov_b32_e32 v69, 0
	v_lshl_add_u64 v[68:69], s[10:11], 0, v[68:69]
	v_lshl_add_u64 v[68:69], v[162:163], 1, v[68:69]
	global_load_dwordx4 v[82:85], v[68:69], off
	global_load_dwordx4 v[86:89], v[68:69], off offset:32
	global_load_dwordx4 v[90:93], v[68:69], off offset:64
	global_load_dwordx4 v[94:97], v[68:69], off offset:96
	global_load_dwordx4 v[98:101], v[68:69], off offset:128
	global_load_dwordx4 v[102:105], v[68:69], off offset:160
	global_load_dwordx4 v[106:109], v[68:69], off offset:192
	global_load_dwordx4 v[110:113], v[68:69], off offset:224
mk_p2b_q_skip:
	s_waitcnt lgkmcnt(0)
	v_mfma_f32_32x32x16_fp8_fp8 v[66:81], v[66:67], v[120:121], 0
	v_add_u32_e32 v0, s4, v202
	v_cvt_f32_i32_e32 v0, v0
	s_cmp_lg_u32 s15, 64
	s_cselect_b64 s[6:7], -1, 0
	s_or_b64 s[6:7], s[74:75], s[6:7]
	v_add_f32_e32 v0, 0xc1000000, v0
	s_mov_b64 s[4:5], -1
	v_mfma_f32_32x32x16_fp8_fp8 v[66:81], v[150:151], v[122:123], v[66:81]
	s_and_b64 vcc, exec, s[6:7]
	v_mfma_f32_32x32x16_fp8_fp8 v[66:81], v[148:149], v[124:125], v[66:81]
	v_add_f32_e32 v148, 0x41000000, v0
	v_mfma_f32_32x32x16_fp8_fp8 v[66:81], v[146:147], v[126:127], v[66:81]
	v_mfma_f32_32x32x16_fp8_fp8 v[66:81], v[144:145], v[128:129], v[66:81]
	v_mfma_f32_32x32x16_fp8_fp8 v[66:81], v[138:139], v[130:131], v[66:81]
	v_mfma_f32_32x32x16_fp8_fp8 v[66:81], v[140:141], v[132:133], v[66:81]
	v_mfma_f32_32x32x16_fp8_fp8 v[66:81], v[142:143], v[134:135], v[66:81]
	s_cbranch_vccz .LBB0_495
	s_andn2_b64 vcc, exec, s[74:75]
	s_cbranch_vccnz .LBB0_487
	v_add_f32_e32 v139, 0x41100000, v0
	v_cmp_ge_f32_e32 vcc, v139, v117
	v_cmp_le_f32_e64 s[6:7], v139, v119
	v_and_b32_e32 v138, 0x7fffffff, v148
	v_and_b32_e32 v139, 0x7fffffff, v139
	v_cmp_ge_f32_e64 s[4:5], v148, v118
	v_cmp_le_f32_e64 s[8:9], v148, v116
	s_nop 1
	v_pk_fma_f32 v[138:139], v[114:115], v[138:139], v[66:67] neg_lo:[1,0,0] neg_hi:[1,0,0]
	s_and_b64 vcc, vcc, s[6:7]
	v_cndmask_b32_e32 v139, v245, v139, vcc
	s_and_b64 vcc, s[4:5], s[8:9]
	v_pk_add_f32 v[140:141], v[0:1], s[12:13] op_sel_hi:[0,1]
	v_cndmask_b32_e32 v138, v245, v138, vcc
	v_cmp_ge_f32_e32 vcc, v141, v117
	v_cmp_ge_f32_e64 s[4:5], v140, v118
	v_cmp_le_f32_e64 s[6:7], v141, v119
	v_cmp_le_f32_e64 s[8:9], v140, v116
	v_and_b32_e32 v141, 0x7fffffff, v141
	v_and_b32_e32 v140, 0x7fffffff, v140
	v_pk_fma_f32 v[140:141], v[114:115], v[140:141], v[68:69] neg_lo:[1,0,0] neg_hi:[1,0,0]
	s_and_b64 vcc, vcc, s[6:7]
	v_cndmask_b32_e32 v141, v245, v141, vcc
	s_and_b64 vcc, s[4:5], s[8:9]
	v_max3_f32 v142, v138, s92, v139
	v_cndmask_b32_e32 v140, v245, v140, vcc
	v_max3_f32 v144, v142, v140, v141
	v_pk_add_f32 v[142:143], v[0:1], s[16:17] op_sel_hi:[0,1]
	v_cmp_ge_f32_e32 vcc, v143, v117
	v_cmp_ge_f32_e64 s[4:5], v142, v118
	v_cmp_le_f32_e64 s[6:7], v143, v119
	v_cmp_le_f32_e64 s[8:9], v142, v116
	v_and_b32_e32 v143, 0x7fffffff, v143
	v_and_b32_e32 v142, 0x7fffffff, v142
	v_pk_fma_f32 v[142:143], v[114:115], v[142:143], v[70:71] neg_lo:[1,0,0] neg_hi:[1,0,0]
	s_and_b64 vcc, vcc, s[6:7]
	v_cndmask_b32_e32 v143, v245, v143, vcc
	s_and_b64 vcc, s[4:5], s[8:9]
	v_cndmask_b32_e32 v142, v245, v142, vcc
	v_max3_f32 v146, v144, v142, v143
	v_pk_add_f32 v[144:145], v[0:1], s[18:19] op_sel_hi:[0,1]
	v_cmp_ge_f32_e32 vcc, v145, v117
	v_cmp_ge_f32_e64 s[4:5], v144, v118
	v_cmp_le_f32_e64 s[6:7], v145, v119
	v_cmp_le_f32_e64 s[8:9], v144, v116
	v_and_b32_e32 v145, 0x7fffffff, v145
	v_and_b32_e32 v144, 0x7fffffff, v144
	v_pk_fma_f32 v[144:145], v[114:115], v[144:145], v[72:73] neg_lo:[1,0,0] neg_hi:[1,0,0]
	s_and_b64 vcc, vcc, s[6:7]
	v_cndmask_b32_e32 v145, v245, v145, vcc
	s_and_b64 vcc, s[4:5], s[8:9]
	v_cndmask_b32_e32 v144, v245, v144, vcc
	v_max3_f32 v149, v146, v144, v145
	v_pk_add_f32 v[146:147], v[0:1], s[20:21] op_sel_hi:[0,1]
	v_cmp_ge_f32_e32 vcc, v147, v117
	v_cmp_ge_f32_e64 s[4:5], v146, v118
	v_cmp_le_f32_e64 s[6:7], v147, v119
	v_cmp_le_f32_e64 s[8:9], v146, v116
	v_and_b32_e32 v147, 0x7fffffff, v147
	v_and_b32_e32 v146, 0x7fffffff, v146
	v_pk_fma_f32 v[146:147], v[114:115], v[146:147], v[74:75] neg_lo:[1,0,0] neg_hi:[1,0,0]
	s_and_b64 vcc, vcc, s[6:7]
	v_cndmask_b32_e32 v147, v245, v147, vcc
	s_and_b64 vcc, s[4:5], s[8:9]
	v_pk_add_f32 v[150:151], v[0:1], s[22:23] op_sel_hi:[0,1]
	v_cndmask_b32_e32 v146, v245, v146, vcc
	v_cmp_ge_f32_e32 vcc, v151, v117
	v_cmp_ge_f32_e64 s[4:5], v150, v118
	v_cmp_le_f32_e64 s[6:7], v151, v119
	v_cmp_le_f32_e64 s[8:9], v150, v116
	v_and_b32_e32 v151, 0x7fffffff, v151
	v_and_b32_e32 v150, 0x7fffffff, v150
	v_pk_fma_f32 v[150:151], v[114:115], v[150:151], v[76:77] neg_lo:[1,0,0] neg_hi:[1,0,0]
	s_and_b64 vcc, vcc, s[6:7]
	v_cndmask_b32_e32 v151, v245, v151, vcc
	s_and_b64 vcc, s[4:5], s[8:9]
	v_pk_add_f32 v[152:153], v[0:1], s[24:25] op_sel_hi:[0,1]
	v_cndmask_b32_e32 v150, v245, v150, vcc
	v_cmp_ge_f32_e32 vcc, v153, v117
	v_cmp_ge_f32_e64 s[4:5], v152, v118
	v_cmp_le_f32_e64 s[6:7], v153, v119
	v_cmp_le_f32_e64 s[8:9], v152, v116
	v_and_b32_e32 v153, 0x7fffffff, v153
	v_and_b32_e32 v152, 0x7fffffff, v152
	v_pk_fma_f32 v[152:153], v[114:115], v[152:153], v[78:79] neg_lo:[1,0,0] neg_hi:[1,0,0]
	s_and_b64 vcc, vcc, s[6:7]
	v_cndmask_b32_e32 v153, v245, v153, vcc
	s_and_b64 vcc, s[4:5], s[8:9]
	v_pk_add_f32 v[154:155], v[0:1], s[26:27] op_sel_hi:[0,1]
	v_cndmask_b32_e32 v152, v245, v152, vcc
	v_cmp_ge_f32_e32 vcc, v155, v117
	v_cmp_ge_f32_e64 s[4:5], v154, v118
	v_cmp_le_f32_e64 s[6:7], v155, v119
	v_cmp_le_f32_e64 s[8:9], v154, v116
	v_and_b32_e32 v155, 0x7fffffff, v155
	v_and_b32_e32 v154, 0x7fffffff, v154
	v_max3_f32 v149, v149, v146, v147
	v_pk_fma_f32 v[154:155], v[114:115], v[154:155], v[80:81] neg_lo:[1,0,0] neg_hi:[1,0,0]
	s_and_b64 vcc, vcc, s[6:7]
	v_max3_f32 v149, v149, v150, v151
	v_cndmask_b32_e32 v155, v245, v155, vcc
	s_and_b64 vcc, s[4:5], s[8:9]
	v_max3_f32 v149, v149, v152, v153
	v_cndmask_b32_e32 v154, v245, v154, vcc
	v_max3_f32 v161, v149, v154, v155
	s_mov_b64 s[4:5], 0

; __device__ __forceinline__ void attn_unit(const bool FINAL, const bool HN, LAS unsigned char* wl, const bf16_t* qb, const bf16_t* kb, const bf16_t* vb, int tq0, int dil, float sl, bf16x8 (&qr)[8], const bf16_t* nqb, const bf16_t* nkb, const bf16_t* nvb, int ntq0, int ndil, ...
;     ...
;         if (n < 4 || HN) asm volatile("s_waitcnt vmcnt(4)" ::: "memory");
;         else asm volatile("s_waitcnt vmcnt(0)" ::: "memory");
.LBB0_503:
	s_andn2_b64 vcc, exec, s[4:5]
	s_cbranch_vccnz .LBB0_505
	s_cmpk_eq_i32 s15, 0x80
	s_cbranch_scc1 mk_p2b_w12
	s_waitcnt vmcnt(4)
	s_branch .LBB0_505
mk_p2b_w12:
	s_waitcnt vmcnt(12)

; #define GAS __attribute__((address_space(1)))
; #define LAS __attribute__((address_space(3)))
; __device__ __forceinline__ unsigned cvtpk(float lo, float hi) { unsigned r; asm volatile("v_cvt_pk_bf16_f32 %0, %1, %2" : "=v"(r) : "v"(lo), "v"(hi)); return r; }
; __device__ __forceinline__ void attn_unit(const bool FINAL, const bool HN, LAS unsigned char* wl, const bf16_t* qb, const bf16_t* kb, const bf16_t* vb, int tq0, int dil, float sl, bf16x8 (&qr)[8], const bf16_t* nqb, const bf16_t* nkb, const bf16_t* nvb, int ntq0, int ndil, ...
;     ...
;     if (HN) at_load_q(qr, nqb, ntq0, ndil, lane);
;     const int tq = tq0 + dil * r32;
;     v4u a0[8], a1v[8];
;     if (FINAL) {
; #pragma unroll
;         for (int i = 0; i < 8; ++i) { const int row = 4 * i + rr0, c = cs ^ (row & 15); const size_t off = (size_t)(tq0 + dil * row) * 128 + 8 * c;
;             a0[i] = __builtin_nontemporal_load((const GAS v4u*)(part0 + off)); a1v[i] = __builtin_nontemporal_load((const GAS v4u*)(part1 + off)); } }
;     float osc, c1 = 0.f, c2 = 0.f;
;     if (!FINAL) { osc = 1.0f / l_run; if (hi == 0) *(GAS f32x2*)(ml + (size_t)tq * 2) = (f32x2){m_run, l_run}; }
;     else {
;         const f32x2 s1 = st1, s2 = st2;
;         const float M = fmaxf(fmaxf(s1.x, s2.x), m_run);
;         const float a1 = __builtin_amdgcn_exp2f(s1.x - M) * s1.y, a2 = __builtin_amdgcn_exp2f(s2.x - M) * s2.y, a3 = __builtin_amdgcn_exp2f(m_run - M);
;         const float inv = 1.0f / (a1 + a2 + a3 * l_run);
;         c1 = a1 * inv; c2 = a2 * inv; osc = a3 * inv;
;     }
;     {
;         LAS unsigned char* wrow = vbuf + r32 * 256 + hi * 8; const int qx = r32 & 15;
; #pragma unroll
;         for (int d0 = 0; d0 < 4; ++d0)
; #pragma unroll
;             for (int g4 = 0; g4 < 4; ++g4) { u32x2 w; w.x = cvtpk(oT[d0][4 * g4] * osc, oT[d0][4 * g4 + 1] * osc); w.y = cvtpk(oT[d0][4 * g4 + 2] * osc, oT[d0][4 * g4 + 3] * osc);
;                 *(LAS u32x2*)(wrow + (((4 * d0 + g4) ^ qx) << 4)) = w; }
.LBB0_513:
	s_and_b64 vcc, exec, s[46:47]
	s_cbranch_vccz .LBB0_515
.LBB0_515:
	v_add_u32_e32 v196, s94, v201
	v_ashrrev_i32_e32 v197, 31, v196
	v_lshlrev_b64 v[66:67], 8, v[196:197]
	v_lshlrev_b32_e32 v0, 1, v164
	v_or_b32_e32 v66, v66, v0
	v_lshl_add_u64 v[68:69], s[58:59], 0, v[66:67]
	v_lshl_add_u64 v[66:67], s[56:57], 0, v[66:67]
	global_load_dwordx4 v[204:207], v[66:67], off nt
	v_add_u32_e32 v66, 4, v201
	v_add_u32_e32 v194, s94, v66
	v_ashrrev_i32_e32 v195, 31, v194
	v_lshlrev_b64 v[66:67], 8, v[194:195]
	v_lshl_or_b32 v66, v166, 1, v66
	v_add_u32_e32 v192, s94, v199
	global_load_dwordx4 v[154:157], v[68:69], off nt
	v_lshl_add_u64 v[68:69], s[58:59], 0, v[66:67]
	v_lshl_add_u64 v[66:67], s[56:57], 0, v[66:67]
	v_ashrrev_i32_e32 v193, 31, v192
	global_load_dwordx4 v[150:153], v[66:67], off nt
	v_lshlrev_b64 v[66:67], 8, v[192:193]
	v_lshl_or_b32 v66, v168, 1, v66
	v_add_u32_e32 v190, s94, v203
	global_load_dwordx4 v[146:149], v[68:69], off nt
	v_lshl_add_u64 v[68:69], s[58:59], 0, v[66:67]
	v_lshl_add_u64 v[66:67], s[56:57], 0, v[66:67]
	v_ashrrev_i32_e32 v191, 31, v190
	global_load_dwordx4 v[142:145], v[66:67], off nt
	v_lshlrev_b64 v[66:67], 8, v[190:191]
	v_lshl_or_b32 v66, v170, 1, v66
	global_load_dwordx4 v[138:141], v[68:69], off nt
	v_lshl_add_u64 v[68:69], s[58:59], 0, v[66:67]
	v_lshl_add_u64 v[66:67], s[56:57], 0, v[66:67]
	global_load_dwordx4 v[134:137], v[66:67], off nt
	v_add_u32_e32 v66, 16, v201
	v_add_u32_e32 v188, s94, v66
	v_ashrrev_i32_e32 v189, 31, v188
	v_lshlrev_b64 v[66:67], 8, v[188:189]
	v_or_b32_e32 v66, v66, v0
	v_add_u32_e32 v0, 20, v201
	v_add_u32_e32 v186, s94, v0
	global_load_dwordx4 v[130:133], v[68:69], off nt
	v_lshl_add_u64 v[68:69], s[58:59], 0, v[66:67]
	v_lshl_add_u64 v[66:67], s[56:57], 0, v[66:67]
	v_ashrrev_i32_e32 v187, 31, v186
	global_load_dwordx4 v[126:129], v[66:67], off nt
	v_lshlrev_b64 v[66:67], 8, v[186:187]
	v_lshl_or_b32 v66, v172, 1, v66
	v_add_u32_e32 v184, s94, v208
	global_load_dwordx4 v[122:125], v[68:69], off nt
	v_lshl_add_u64 v[68:69], s[58:59], 0, v[66:67]
	v_lshl_add_u64 v[66:67], s[56:57], 0, v[66:67]
	v_ashrrev_i32_e32 v185, 31, v184
	global_load_dwordx4 v[118:121], v[66:67], off nt
	v_lshlrev_b64 v[66:67], 8, v[184:185]
	v_lshl_or_b32 v66, v174, 1, v66
	global_load_dwordx4 v[114:117], v[68:69], off nt
	v_lshl_add_u64 v[68:69], s[58:59], 0, v[66:67]
	s_waitcnt vmcnt(0)
	v_max3_f32 v0, v180, v178, v161
	global_load_dwordx4 v[74:77], v[68:69], off nt
	v_sub_f32_e32 v68, v180, v0
	v_exp_f32_e32 v158, v68
	v_sub_f32_e32 v68, v178, v0
	v_sub_f32_e32 v0, v161, v0
	v_exp_f32_e32 v159, v0
	v_exp_f32_e32 v0, v68
	v_add_u32_e32 v182, s94, v209
	v_ashrrev_i32_e32 v183, 31, v182
	v_mov_b32_e32 v70, v181
	v_lshlrev_b64 v[72:73], 8, v[182:183]
	v_pk_mul_f32 v[160:161], v[70:71], v[158:159]
	v_lshl_add_u64 v[66:67], s[56:57], 0, v[66:67]
	v_lshl_or_b32 v72, v176, 1, v72
	v_fma_f32 v70, v179, v0, v160
	global_load_dwordx4 v[78:81], v[66:67], off nt
	v_lshl_add_u64 v[66:67], s[58:59], 0, v[72:73]
	v_add_f32_e32 v158, v70, v161
	v_lshl_add_u64 v[70:71], s[56:57], 0, v[72:73]
	global_load_dwordx4 v[66:69], v[66:67], off nt
	v_div_scale_f32 v161, s[4:5], v158, v158, 1.0
	global_load_dwordx4 v[70:73], v[70:71], off nt
	v_rcp_f32_e32 v178, v161
	v_mul_f32_e32 v179, v179, v0
	v_fma_f32 v0, -v161, v178, 1.0
	v_fmac_f32_e32 v178, v0, v178
	v_div_scale_f32 v0, vcc, 1.0, v158, 1.0
	v_mul_f32_e32 v180, v0, v178
	v_fma_f32 v181, -v161, v180, v0
	v_fmac_f32_e32 v180, v181, v178
	v_fma_f32 v0, -v161, v180, v0
	v_div_fmas_f32 v0, v0, v178, v180
	v_div_fixup_f32 v158, v0, v158, 1.0
	v_mul_f32_e32 v0, v160, v158
	v_mul_f32_e32 v178, v179, v158
	v_mul_f32_e32 v158, v159, v158
	v_mul_f32_e32 v50, v158, v50
	v_mul_f32_e32 v51, v158, v51
	v_cvt_pk_bf16_f32 v50, v50, v51
	v_mul_f32_e32 v51, v158, v52
	v_mul_f32_e32 v52, v158, v53
	v_cvt_pk_bf16_f32 v51, v51, v52
	v_add_u32_e32 v52, v210, v211
	ds_write_b64 v52, v[50:51] offset:8192
	v_mul_f32_e32 v50, v158, v54
	v_mul_f32_e32 v51, v158, v55
	v_cvt_pk_bf16_f32 v50, v50, v51
	v_mul_f32_e32 v51, v158, v56
	v_mul_f32_e32 v52, v158, v57
	v_cvt_pk_bf16_f32 v51, v51, v52
	ds_write_b64 v221, v[50:51] offset:8192
	v_mul_f32_e32 v50, v158, v58
	v_mul_f32_e32 v51, v158, v59
	v_cvt_pk_bf16_f32 v50, v50, v51
	v_mul_f32_e32 v51, v158, v60
	v_mul_f32_e32 v52, v158, v61
	v_cvt_pk_bf16_f32 v51, v51, v52
	ds_write_b64 v222, v[50:51] offset:8192
	v_mul_f32_e32 v50, v158, v62
	v_mul_f32_e32 v51, v158, v63
	v_cvt_pk_bf16_f32 v50, v50, v51
	v_mul_f32_e32 v51, v158, v64
	v_mul_f32_e32 v34, v158, v34
	v_mul_f32_e32 v35, v158, v35
	v_mul_f32_e32 v52, v158, v65
	v_cvt_pk_bf16_f32 v51, v51, v52
	ds_write_b64 v223, v[50:51] offset:8192
	v_cvt_pk_bf16_f32 v34, v34, v35
	v_mul_f32_e32 v35, v158, v36
	v_mul_f32_e32 v36, v158, v37
	v_cvt_pk_bf16_f32 v35, v35, v36
	ds_write_b64 v224, v[34:35] offset:8192
	v_mul_f32_e32 v34, v158, v38
	v_mul_f32_e32 v35, v158, v39
	v_cvt_pk_bf16_f32 v34, v34, v35
	v_mul_f32_e32 v35, v158, v40
	v_mul_f32_e32 v36, v158, v41
	v_cvt_pk_bf16_f32 v35, v35, v36
	ds_write_b64 v225, v[34:35] offset:8192
	v_mul_f32_e32 v34, v158, v42
	v_mul_f32_e32 v35, v158, v43
	v_cvt_pk_bf16_f32 v34, v34, v35
	v_mul_f32_e32 v35, v158, v44
	v_mul_f32_e32 v36, v158, v45
	v_cvt_pk_bf16_f32 v35, v35, v36
	ds_write_b64 v226, v[34:35] offset:8192
	v_mul_f32_e32 v34, v158, v46
	v_mul_f32_e32 v35, v158, v47
	v_cvt_pk_bf16_f32 v34, v34, v35
	v_mul_f32_e32 v35, v158, v48
	v_mul_f32_e32 v18, v158, v18
	v_mul_f32_e32 v19, v158, v19
	v_mul_f32_e32 v36, v158, v49
	v_cvt_pk_bf16_f32 v35, v35, v36
	ds_write_b64 v227, v[34:35] offset:8192
	v_cvt_pk_bf16_f32 v18, v18, v19
	v_mul_f32_e32 v19, v158, v20
; __device__ __forceinline__ unsigned pk_fp8x4(const f32x4 v) { int r = __builtin_amdgcn_cvt_pk_fp8_f32(v[0], v[1], 0, false); r = __builtin_amdgcn_cvt_pk_fp8_f32(v[2], v[3], r, true); return (unsigned)r; }
; #define GAS __attribute__((address_space(1)))
; #define LAS __attribute__((address_space(3)))
; __device__ __forceinline__ unsigned cvtpk(float lo, float hi) { unsigned r; asm volatile("v_cvt_pk_bf16_f32 %0, %1, %2" : "=v"(r) : "v"(lo), "v"(hi)); return r; }
; #define SBAR() __builtin_amdgcn_sched_barrier(0)
; #define AT_MIX(F, J) do { f8[2 * J] = w1 * bf2f(a0[i].F & 0xffffu) + w2 * bf2f(a1v[i].F & 0xffffu) + bf2f(o.F & 0xffffu); \
;                 f8[2 * J + 1] = w1 * bf2f(a0[i].F >> 16) + w2 * bf2f(a1v[i].F >> 16) + bf2f(o.F >> 16); } while (0)
; __device__ __forceinline__ void attn_unit(const bool FINAL, const bool HN, LAS unsigned char* wl, const bf16_t* qb, const bf16_t* kb, const bf16_t* vb, int tq0, int dil, float sl, bf16x8 (&qr)[8], const bf16_t* nqb, const bf16_t* nkb, const bf16_t* nvb, int ntq0, int ndil, ...
;     ...
;             for (int g4 = 0; g4 < 4; ++g4) { u32x2 w; w.x = cvtpk(oT[d0][4 * g4] * osc, oT[d0][4 * g4 + 1] * osc); w.y = cvtpk(oT[d0][4 * g4 + 2] * osc, oT[d0][4 * g4 + 3] * osc);
;                 *(LAS u32x2*)(wrow + (((4 * d0 + g4) ^ qx) << 4)) = w; }
;     }
;     asm volatile("s_waitcnt lgkmcnt(0)" ::: "memory"); SBAR();
;     if (!FINAL) {
; #pragma unroll
;         for (int i = 0; i < 8; ++i) a0[i] = *(const LAS v4u*)(vbuf + (4 * i + rr0) * 256 + cs * 16);
; #pragma unroll
;         for (int i = 0; i < 8; ++i) { const int row = 4 * i + rr0, c = cs ^ (row & 15);
;             *(GAS v4u*)(part + (size_t)(tq0 + dil * row) * 128 + 8 * c) = a0[i]; }
;     } else {
; #pragma unroll
;         for (int i = 0; i < 8; ++i) { const int row = 4 * i + rr0, c = cs ^ (row & 15);
;             const float w1 = __shfl(c1, row), w2 = __shfl(c2, row);
;             const v4u o = *(const LAS v4u*)(vbuf + row * 256 + cs * 16);
;             float f8[8];
;     ...
;             AT_MIX(x, 0); AT_MIX(y, 1); AT_MIX(z, 2); AT_MIX(w, 3);
;     ...
;             u32x2 r8; r8.x = pg8::pk_fp8x4((f32x4){f8[0], f8[1], f8[2], f8[3]}); r8.y = pg8::pk_fp8x4((f32x4){f8[4], f8[5], f8[6], f8[7]});
;             *(GAS u32x2*)((GAS unsigned char*)yout + (size_t)(tq0 + dil * row) * 3072 + 8 * c) = r8; }
	v_mul_f32_e32 v20, v158, v21
	v_cvt_pk_bf16_f32 v19, v19, v20
	ds_write_b64 v228, v[18:19] offset:8192
	v_mul_f32_e32 v18, v158, v22
	v_mul_f32_e32 v19, v158, v23
	v_cvt_pk_bf16_f32 v18, v18, v19
	v_mul_f32_e32 v19, v158, v24
	v_mul_f32_e32 v20, v158, v25
	v_cvt_pk_bf16_f32 v19, v19, v20
	ds_write_b64 v229, v[18:19] offset:8192
	v_mul_f32_e32 v18, v158, v26
	v_mul_f32_e32 v19, v158, v27
	v_cvt_pk_bf16_f32 v18, v18, v19
	v_mul_f32_e32 v19, v158, v28
	v_mul_f32_e32 v20, v158, v29
	v_cvt_pk_bf16_f32 v19, v19, v20
	ds_write_b64 v230, v[18:19] offset:8192
	v_mul_f32_e32 v18, v158, v30
	v_mul_f32_e32 v19, v158, v31
	v_cvt_pk_bf16_f32 v18, v18, v19
	v_mul_f32_e32 v19, v158, v32
	v_mul_f32_e32 v2, v158, v2
	v_mul_f32_e32 v3, v158, v3
	v_mul_f32_e32 v20, v158, v33
	v_cvt_pk_bf16_f32 v19, v19, v20
	ds_write_b64 v231, v[18:19] offset:8192
	v_cvt_pk_bf16_f32 v2, v2, v3
	v_mul_f32_e32 v3, v158, v4
	v_mul_f32_e32 v4, v158, v5
	v_cvt_pk_bf16_f32 v3, v3, v4
	ds_write_b64 v232, v[2:3] offset:8192
	v_mul_f32_e32 v2, v158, v6
	v_mul_f32_e32 v3, v158, v7
	v_cvt_pk_bf16_f32 v2, v2, v3
	v_mul_f32_e32 v3, v158, v8
	v_mul_f32_e32 v4, v158, v9
	v_cvt_pk_bf16_f32 v3, v3, v4
	ds_write_b64 v233, v[2:3] offset:8192
	v_mul_f32_e32 v2, v158, v10
	v_mul_f32_e32 v3, v158, v11
	v_cvt_pk_bf16_f32 v2, v2, v3
	v_mul_f32_e32 v3, v158, v12
	v_mul_f32_e32 v4, v158, v13
	v_cvt_pk_bf16_f32 v3, v3, v4
	ds_write_b64 v234, v[2:3] offset:8192
	v_mul_f32_e32 v2, v158, v14
	v_mul_f32_e32 v3, v158, v15
	v_cvt_pk_bf16_f32 v2, v2, v3
	v_mul_f32_e32 v3, v158, v16
	v_mul_f32_e32 v4, v158, v17
	v_cvt_pk_bf16_f32 v3, v3, v4
	ds_write_b64 v235, v[2:3] offset:8192
	s_waitcnt lgkmcnt(0)
	ds_read_b128 v[2:5], v236 offset:8192
	ds_read_b128 v[6:9], v237 offset:8192
	ds_bpermute_b32 v10, v246, v0
	ds_bpermute_b32 v11, v246, v178
	s_waitcnt lgkmcnt(0)
	v_lshlrev_b32_e32 v12, 16, v2
	v_and_b32_e32 v13, 0xffff0000, v2
	v_lshlrev_b32_e32 v14, 16, v3
	v_and_b32_e32 v15, 0xffff0000, v3
	v_lshlrev_b32_e32 v3, 16, v204
	v_lshlrev_b32_e32 v2, 16, v154
	v_pk_mul_f32 v[2:3], v[2:3], v[10:11]
	v_lshlrev_b32_e32 v16, 16, v4
	v_add_f32_e32 v2, v2, v3
	v_add_f32_e32 v12, v2, v12
	v_and_b32_e32 v3, 0xffff0000, v204
	v_and_b32_e32 v2, 0xffff0000, v154
	v_pk_mul_f32 v[2:3], v[2:3], v[10:11]
	v_and_b32_e32 v4, 0xffff0000, v4
	v_add_f32_e32 v2, v2, v3
	v_add_f32_e32 v13, v2, v13
	v_lshlrev_b32_e32 v3, 16, v205
	v_lshlrev_b32_e32 v2, 16, v155
	v_pk_mul_f32 v[2:3], v[2:3], v[10:11]
	s_nop 0
	v_add_f32_e32 v2, v2, v3
	v_add_f32_e32 v14, v2, v14
	v_and_b32_e32 v3, 0xffff0000, v205
	v_and_b32_e32 v2, 0xffff0000, v155
	v_pk_mul_f32 v[2:3], v[2:3], v[10:11]
	s_nop 0
	v_add_f32_e32 v2, v2, v3
	v_add_f32_e32 v15, v2, v15
	v_lshlrev_b32_e32 v3, 16, v206
	v_lshlrev_b32_e32 v2, 16, v156
	v_pk_mul_f32 v[2:3], v[2:3], v[10:11]
	s_nop 0
	v_add_f32_e32 v2, v2, v3
	v_add_f32_e32 v16, v2, v16
	v_and_b32_e32 v3, 0xffff0000, v206
	v_and_b32_e32 v2, 0xffff0000, v156
	v_pk_mul_f32 v[2:3], v[2:3], v[10:11]
	s_nop 0
	v_add_f32_e32 v2, v2, v3
	v_add_f32_e32 v4, v2, v4
	v_lshlrev_b32_e32 v3, 16, v207
	v_lshlrev_b32_e32 v2, 16, v157
	v_pk_mul_f32 v[2:3], v[2:3], v[10:11]
	s_nop 0
	v_add_f32_e32 v2, v2, v3
	v_lshlrev_b32_e32 v3, 16, v5
	v_add_f32_e32 v17, v2, v3
	v_and_b32_e32 v3, 0xffff0000, v207
	v_and_b32_e32 v2, 0xffff0000, v157
	v_pk_mul_f32 v[2:3], v[2:3], v[10:11]
	v_mov_b32_e32 v10, 0
	v_mov_b32_e32 v11, 0
	v_cvt_pk_fp8_f32 v10, v12, v13
	v_cvt_pk_fp8_f32 v11, v16, v4
	v_add_f32_e32 v2, v2, v3
	v_and_b32_e32 v3, 0xffff0000, v5
	v_add_f32_e32 v2, v2, v3
	v_cvt_pk_fp8_f32 v10, v14, v15 op_sel:[0,0,1]
	v_cvt_pk_fp8_f32 v11, v17, v2 op_sel:[0,0,1]
	v_mov_b64_e32 v[2:3], s[54:55]
	v_mad_i64_i32 v[4:5], s[4:5], v196, s97, v[2:3]
	v_lshl_add_u64 v[4:5], v[4:5], 0, v[164:165]
	global_store_dwordx2 v[4:5], v[10:11], off
	ds_bpermute_b32 v4, v247, v0
	ds_bpermute_b32 v5, v247, v178
	v_lshlrev_b32_e32 v10, 16, v6
	v_and_b32_e32 v11, 0xffff0000, v6
	v_lshlrev_b32_e32 v12, 16, v7
	v_and_b32_e32 v13, 0xffff0000, v7
	v_lshlrev_b32_e32 v7, 16, v150
	v_lshlrev_b32_e32 v6, 16, v146
	s_waitcnt lgkmcnt(0)
	v_pk_mul_f32 v[6:7], v[6:7], v[4:5]
	v_lshlrev_b32_e32 v14, 16, v8
	v_add_f32_e32 v6, v6, v7
	v_add_f32_e32 v15, v6, v10
	v_and_b32_e32 v7, 0xffff0000, v150
	v_and_b32_e32 v6, 0xffff0000, v146
	v_pk_mul_f32 v[6:7], v[6:7], v[4:5]
	v_and_b32_e32 v8, 0xffff0000, v8
	v_add_f32_e32 v6, v6, v7
	v_add_f32_e32 v11, v6, v11
	v_lshlrev_b32_e32 v7, 16, v151
	v_lshlrev_b32_e32 v6, 16, v147
	v_pk_mul_f32 v[6:7], v[6:7], v[4:5]
	v_mov_b32_e32 v10, 0
	v_add_f32_e32 v6, v6, v7
	v_add_f32_e32 v12, v6, v12
	v_and_b32_e32 v7, 0xffff0000, v151
	v_and_b32_e32 v6, 0xffff0000, v147
	v_pk_mul_f32 v[6:7], v[6:7], v[4:5]
	v_cvt_pk_fp8_f32 v10, v15, v11
	v_add_f32_e32 v6, v6, v7
	v_add_f32_e32 v13, v6, v13
	v_lshlrev_b32_e32 v7, 16, v152
	v_lshlrev_b32_e32 v6, 16, v148
	v_pk_mul_f32 v[6:7], v[6:7], v[4:5]
	v_mov_b32_e32 v11, 0
	v_add_f32_e32 v6, v6, v7
	v_add_f32_e32 v14, v6, v14
	v_and_b32_e32 v7, 0xffff0000, v152
	v_and_b32_e32 v6, 0xffff0000, v148
	v_pk_mul_f32 v[6:7], v[6:7], v[4:5]
	v_cvt_pk_fp8_f32 v10, v12, v13 op_sel:[0,0,1]
	v_add_f32_e32 v6, v6, v7
	v_add_f32_e32 v8, v6, v8
	v_lshlrev_b32_e32 v7, 16, v153
	v_lshlrev_b32_e32 v6, 16, v149
	v_pk_mul_f32 v[6:7], v[6:7], v[4:5]
	v_cvt_pk_fp8_f32 v11, v14, v8
	v_add_f32_e32 v6, v6, v7
	v_lshlrev_b32_e32 v7, 16, v9
	v_add_f32_e32 v16, v6, v7
	v_and_b32_e32 v7, 0xffff0000, v153
	v_and_b32_e32 v6, 0xffff0000, v149
	v_pk_mul_f32 v[4:5], v[6:7], v[4:5]
	ds_bpermute_b32 v12, v248, v0
	v_add_f32_e32 v4, v4, v5
	v_and_b32_e32 v5, 0xffff0000, v9
	v_add_f32_e32 v4, v4, v5
	v_cvt_pk_fp8_f32 v11, v16, v4 op_sel:[0,0,1]
	v_mad_i64_i32 v[4:5], s[4:5], v194, s97, v[2:3]
	v_lshl_add_u64 v[8:9], v[4:5], 0, v[166:167]
	ds_read_b128 v[4:7], v238 offset:8192
	ds_bpermute_b32 v13, v248, v178
	global_store_dwordx2 v[8:9], v[10:11], off
	ds_read_b128 v[8:11], v239 offset:8192
	s_waitcnt lgkmcnt(2)
; __device__ __forceinline__ unsigned pk_fp8x4(const f32x4 v) { int r = __builtin_amdgcn_cvt_pk_fp8_f32(v[0], v[1], 0, false); r = __builtin_amdgcn_cvt_pk_fp8_f32(v[2], v[3], r, true); return (unsigned)r; }
; #define GAS __attribute__((address_space(1)))
; #define LAS __attribute__((address_space(3)))
; #define AT_MIX(F, J) do { f8[2 * J] = w1 * bf2f(a0[i].F & 0xffffu) + w2 * bf2f(a1v[i].F & 0xffffu) + bf2f(o.F & 0xffffu); \
;                 f8[2 * J + 1] = w1 * bf2f(a0[i].F >> 16) + w2 * bf2f(a1v[i].F >> 16) + bf2f(o.F >> 16); } while (0)
; __device__ __forceinline__ void attn_unit(const bool FINAL, const bool HN, LAS unsigned char* wl, const bf16_t* qb, const bf16_t* kb, const bf16_t* vb, int tq0, int dil, float sl, bf16x8 (&qr)[8], const bf16_t* nqb, const bf16_t* nkb, const bf16_t* nvb, int ntq0, int ndil, ...
;     ...
;     } else {
; #pragma unroll
;         for (int i = 0; i < 8; ++i) { const int row = 4 * i + rr0, c = cs ^ (row & 15);
;             const float w1 = __shfl(c1, row), w2 = __shfl(c2, row);
;             const v4u o = *(const LAS v4u*)(vbuf + row * 256 + cs * 16);
;             float f8[8];
;     ...
;             AT_MIX(x, 0); AT_MIX(y, 1); AT_MIX(z, 2); AT_MIX(w, 3);
;     ...
;             u32x2 r8; r8.x = pg8::pk_fp8x4((f32x4){f8[0], f8[1], f8[2], f8[3]}); r8.y = pg8::pk_fp8x4((f32x4){f8[4], f8[5], f8[6], f8[7]});
;             *(GAS u32x2*)((GAS unsigned char*)yout + (size_t)(tq0 + dil * row) * 3072 + 8 * c) = r8; }
	v_lshlrev_b32_e32 v14, 16, v4
	v_and_b32_e32 v15, 0xffff0000, v4
	v_lshlrev_b32_e32 v16, 16, v5
	v_and_b32_e32 v17, 0xffff0000, v5
	v_lshlrev_b32_e32 v5, 16, v142
	v_lshlrev_b32_e32 v4, 16, v138
	s_waitcnt lgkmcnt(1)
	v_pk_mul_f32 v[4:5], v[4:5], v[12:13]
	v_lshlrev_b32_e32 v18, 16, v6
	v_add_f32_e32 v4, v4, v5
	v_add_f32_e32 v14, v4, v14
	v_and_b32_e32 v5, 0xffff0000, v142
	v_and_b32_e32 v4, 0xffff0000, v138
	v_pk_mul_f32 v[4:5], v[4:5], v[12:13]
	v_and_b32_e32 v6, 0xffff0000, v6
	v_add_f32_e32 v4, v4, v5
	v_add_f32_e32 v15, v4, v15
	v_lshlrev_b32_e32 v5, 16, v143
	v_lshlrev_b32_e32 v4, 16, v139
	v_pk_mul_f32 v[4:5], v[4:5], v[12:13]
	s_nop 0
	v_add_f32_e32 v4, v4, v5
	v_add_f32_e32 v16, v4, v16
	v_and_b32_e32 v5, 0xffff0000, v143
	v_and_b32_e32 v4, 0xffff0000, v139
	v_pk_mul_f32 v[4:5], v[4:5], v[12:13]
	s_nop 0
	v_add_f32_e32 v4, v4, v5
	v_add_f32_e32 v17, v4, v17
	v_lshlrev_b32_e32 v5, 16, v144
	v_lshlrev_b32_e32 v4, 16, v140
	v_pk_mul_f32 v[4:5], v[4:5], v[12:13]
	s_nop 0
	v_add_f32_e32 v4, v4, v5
	v_add_f32_e32 v18, v4, v18
	v_and_b32_e32 v5, 0xffff0000, v144
	v_and_b32_e32 v4, 0xffff0000, v140
	v_pk_mul_f32 v[4:5], v[4:5], v[12:13]
	s_nop 0
	v_add_f32_e32 v4, v4, v5
	v_add_f32_e32 v6, v4, v6
	v_lshlrev_b32_e32 v5, 16, v145
	v_lshlrev_b32_e32 v4, 16, v141
	v_pk_mul_f32 v[4:5], v[4:5], v[12:13]
	s_nop 0
	v_add_f32_e32 v4, v4, v5
	v_lshlrev_b32_e32 v5, 16, v7
	v_add_f32_e32 v19, v4, v5
	v_and_b32_e32 v5, 0xffff0000, v145
	v_and_b32_e32 v4, 0xffff0000, v141
	v_pk_mul_f32 v[4:5], v[4:5], v[12:13]
	s_waitcnt lgkmcnt(0)
	v_lshlrev_b32_e32 v13, 16, v9
	v_add_f32_e32 v12, v4, v5
	v_mov_b32_e32 v4, 0
	v_mov_b32_e32 v5, 0
	v_cvt_pk_fp8_f32 v4, v14, v15
	v_cvt_pk_fp8_f32 v5, v18, v6
	v_and_b32_e32 v6, 0xffff0000, v7
	v_add_f32_e32 v6, v12, v6
	v_cvt_pk_fp8_f32 v4, v16, v17 op_sel:[0,0,1]
	v_cvt_pk_fp8_f32 v5, v19, v6 op_sel:[0,0,1]
	v_mad_i64_i32 v[6:7], s[4:5], v192, s97, v[2:3]
	v_lshl_add_u64 v[6:7], v[6:7], 0, v[168:169]
	global_store_dwordx2 v[6:7], v[4:5], off
	ds_bpermute_b32 v4, v249, v0
	ds_bpermute_b32 v5, v249, v178
	v_lshlrev_b32_e32 v7, 16, v134
	v_lshlrev_b32_e32 v6, 16, v130
	v_lshlrev_b32_e32 v12, 16, v8
	v_and_b32_e32 v8, 0xffff0000, v8
	s_waitcnt lgkmcnt(0)
	v_pk_mul_f32 v[6:7], v[6:7], v[4:5]
	v_and_b32_e32 v9, 0xffff0000, v9
	v_add_f32_e32 v6, v6, v7
	v_add_f32_e32 v12, v6, v12
	v_and_b32_e32 v7, 0xffff0000, v134
	v_and_b32_e32 v6, 0xffff0000, v130
	v_pk_mul_f32 v[6:7], v[6:7], v[4:5]
	v_lshlrev_b32_e32 v14, 16, v10
	v_add_f32_e32 v6, v6, v7
	v_add_f32_e32 v15, v6, v8
	v_lshlrev_b32_e32 v7, 16, v135
	v_lshlrev_b32_e32 v6, 16, v131
	v_pk_mul_f32 v[6:7], v[6:7], v[4:5]
	v_and_b32_e32 v10, 0xffff0000, v10
	v_add_f32_e32 v6, v6, v7
	v_add_f32_e32 v13, v6, v13
	v_and_b32_e32 v7, 0xffff0000, v135
	v_and_b32_e32 v6, 0xffff0000, v131
	v_pk_mul_f32 v[6:7], v[6:7], v[4:5]
	v_mov_b32_e32 v8, 0
	v_add_f32_e32 v6, v6, v7
	v_add_f32_e32 v16, v6, v9
	v_lshlrev_b32_e32 v7, 16, v136
	v_lshlrev_b32_e32 v6, 16, v132
	v_pk_mul_f32 v[6:7], v[6:7], v[4:5]
	v_mov_b32_e32 v9, 0
	v_add_f32_e32 v6, v6, v7
	v_add_f32_e32 v14, v6, v14
	v_and_b32_e32 v7, 0xffff0000, v136
	v_and_b32_e32 v6, 0xffff0000, v132
	v_pk_mul_f32 v[6:7], v[6:7], v[4:5]
	v_cvt_pk_fp8_f32 v8, v12, v15
	v_add_f32_e32 v6, v6, v7
	v_add_f32_e32 v10, v6, v10
	v_lshlrev_b32_e32 v7, 16, v137
	v_lshlrev_b32_e32 v6, 16, v133
	v_pk_mul_f32 v[6:7], v[6:7], v[4:5]
	v_cvt_pk_fp8_f32 v9, v14, v10
	v_add_f32_e32 v6, v6, v7
	v_lshlrev_b32_e32 v7, 16, v11
	v_add_f32_e32 v17, v6, v7
	v_and_b32_e32 v7, 0xffff0000, v137
	v_and_b32_e32 v6, 0xffff0000, v133
	v_pk_mul_f32 v[4:5], v[6:7], v[4:5]
	v_cvt_pk_fp8_f32 v8, v13, v16 op_sel:[0,0,1]
	v_add_f32_e32 v4, v4, v5
	v_and_b32_e32 v5, 0xffff0000, v11
	v_add_f32_e32 v4, v4, v5
	v_cvt_pk_fp8_f32 v9, v17, v4 op_sel:[0,0,1]
	v_mad_i64_i32 v[4:5], s[4:5], v190, s97, v[2:3]
	v_lshl_add_u64 v[10:11], v[4:5], 0, v[170:171]
	ds_read_b128 v[4:7], v240 offset:8192
	ds_bpermute_b32 v12, v250, v0
	ds_bpermute_b32 v13, v250, v178
	global_store_dwordx2 v[10:11], v[8:9], off
	ds_read_b128 v[8:11], v241 offset:8192
	s_waitcnt lgkmcnt(3)
	v_lshlrev_b32_e32 v14, 16, v4
	v_and_b32_e32 v15, 0xffff0000, v4
	v_lshlrev_b32_e32 v16, 16, v5
	v_and_b32_e32 v17, 0xffff0000, v5
	v_lshlrev_b32_e32 v5, 16, v126
	v_lshlrev_b32_e32 v4, 16, v122
	s_waitcnt lgkmcnt(1)
	v_pk_mul_f32 v[4:5], v[4:5], v[12:13]
	v_lshlrev_b32_e32 v18, 16, v6
	v_add_f32_e32 v4, v4, v5
	v_add_f32_e32 v14, v4, v14
	v_and_b32_e32 v5, 0xffff0000, v126
	v_and_b32_e32 v4, 0xffff0000, v122
	v_pk_mul_f32 v[4:5], v[4:5], v[12:13]
	v_and_b32_e32 v6, 0xffff0000, v6
	v_add_f32_e32 v4, v4, v5
	v_add_f32_e32 v15, v4, v15
	v_lshlrev_b32_e32 v5, 16, v127
	v_lshlrev_b32_e32 v4, 16, v123
	v_pk_mul_f32 v[4:5], v[4:5], v[12:13]
	s_nop 0
	v_add_f32_e32 v4, v4, v5
	v_add_f32_e32 v16, v4, v16
	v_and_b32_e32 v5, 0xffff0000, v127
	v_and_b32_e32 v4, 0xffff0000, v123
	v_pk_mul_f32 v[4:5], v[4:5], v[12:13]
	s_nop 0
	v_add_f32_e32 v4, v4, v5
	v_add_f32_e32 v17, v4, v17
	v_lshlrev_b32_e32 v5, 16, v128
	v_lshlrev_b32_e32 v4, 16, v124
	v_pk_mul_f32 v[4:5], v[4:5], v[12:13]
	s_nop 0
	v_add_f32_e32 v4, v4, v5
	v_add_f32_e32 v18, v4, v18
	v_and_b32_e32 v5, 0xffff0000, v128
	v_and_b32_e32 v4, 0xffff0000, v124
	v_pk_mul_f32 v[4:5], v[4:5], v[12:13]
	s_nop 0
	v_add_f32_e32 v4, v4, v5
	v_add_f32_e32 v6, v4, v6
	v_lshlrev_b32_e32 v5, 16, v129
	v_lshlrev_b32_e32 v4, 16, v125
	v_pk_mul_f32 v[4:5], v[4:5], v[12:13]
	s_nop 0
	v_add_f32_e32 v4, v4, v5
	v_lshlrev_b32_e32 v5, 16, v7
	v_add_f32_e32 v19, v4, v5
	v_and_b32_e32 v5, 0xffff0000, v129
	v_and_b32_e32 v4, 0xffff0000, v125
	v_pk_mul_f32 v[4:5], v[4:5], v[12:13]
	s_waitcnt lgkmcnt(0)
; __device__ __forceinline__ unsigned pk_fp8x4(const f32x4 v) { int r = __builtin_amdgcn_cvt_pk_fp8_f32(v[0], v[1], 0, false); r = __builtin_amdgcn_cvt_pk_fp8_f32(v[2], v[3], r, true); return (unsigned)r; }
; #define GAS __attribute__((address_space(1)))
; #define LAS __attribute__((address_space(3)))
; #define AT_MIX(F, J) do { f8[2 * J] = w1 * bf2f(a0[i].F & 0xffffu) + w2 * bf2f(a1v[i].F & 0xffffu) + bf2f(o.F & 0xffffu); \
;                 f8[2 * J + 1] = w1 * bf2f(a0[i].F >> 16) + w2 * bf2f(a1v[i].F >> 16) + bf2f(o.F >> 16); } while (0)
; __device__ __forceinline__ void attn_unit(const bool FINAL, const bool HN, LAS unsigned char* wl, const bf16_t* qb, const bf16_t* kb, const bf16_t* vb, int tq0, int dil, float sl, bf16x8 (&qr)[8], const bf16_t* nqb, const bf16_t* nkb, const bf16_t* nvb, int ntq0, int ndil, ...
;     ...
;     } else {
; #pragma unroll
;         for (int i = 0; i < 8; ++i) { const int row = 4 * i + rr0, c = cs ^ (row & 15);
;             const float w1 = __shfl(c1, row), w2 = __shfl(c2, row);
;             const v4u o = *(const LAS v4u*)(vbuf + row * 256 + cs * 16);
;             float f8[8];
;     ...
;             AT_MIX(x, 0); AT_MIX(y, 1); AT_MIX(z, 2); AT_MIX(w, 3);
;     ...
;             u32x2 r8; r8.x = pg8::pk_fp8x4((f32x4){f8[0], f8[1], f8[2], f8[3]}); r8.y = pg8::pk_fp8x4((f32x4){f8[4], f8[5], f8[6], f8[7]});
;             *(GAS u32x2*)((GAS unsigned char*)yout + (size_t)(tq0 + dil * row) * 3072 + 8 * c) = r8; }
	v_lshlrev_b32_e32 v13, 16, v9
	v_add_f32_e32 v12, v4, v5
	v_mov_b32_e32 v4, 0
	v_mov_b32_e32 v5, 0
	v_cvt_pk_fp8_f32 v4, v14, v15
	v_cvt_pk_fp8_f32 v5, v18, v6
	v_and_b32_e32 v6, 0xffff0000, v7
	v_add_f32_e32 v6, v12, v6
	v_cvt_pk_fp8_f32 v4, v16, v17 op_sel:[0,0,1]
	v_cvt_pk_fp8_f32 v5, v19, v6 op_sel:[0,0,1]
	v_mad_i64_i32 v[6:7], s[4:5], v188, s97, v[2:3]
	v_lshl_add_u64 v[6:7], v[6:7], 0, v[164:165]
	global_store_dwordx2 v[6:7], v[4:5], off
	ds_bpermute_b32 v4, v251, v0
	ds_bpermute_b32 v5, v251, v178
	v_lshlrev_b32_e32 v7, 16, v118
	v_lshlrev_b32_e32 v6, 16, v114
	v_lshlrev_b32_e32 v12, 16, v8
	v_and_b32_e32 v8, 0xffff0000, v8
	s_waitcnt lgkmcnt(0)
	v_pk_mul_f32 v[6:7], v[6:7], v[4:5]
	v_and_b32_e32 v9, 0xffff0000, v9
	v_add_f32_e32 v6, v6, v7
	v_add_f32_e32 v12, v6, v12
	v_and_b32_e32 v7, 0xffff0000, v118
	v_and_b32_e32 v6, 0xffff0000, v114
	v_pk_mul_f32 v[6:7], v[6:7], v[4:5]
	v_lshlrev_b32_e32 v14, 16, v10
	v_add_f32_e32 v6, v6, v7
	v_add_f32_e32 v15, v6, v8
	v_lshlrev_b32_e32 v7, 16, v119
	v_lshlrev_b32_e32 v6, 16, v115
	v_pk_mul_f32 v[6:7], v[6:7], v[4:5]
	v_and_b32_e32 v10, 0xffff0000, v10
	v_add_f32_e32 v6, v6, v7
	v_add_f32_e32 v13, v6, v13
	v_and_b32_e32 v7, 0xffff0000, v119
	v_and_b32_e32 v6, 0xffff0000, v115
	v_pk_mul_f32 v[6:7], v[6:7], v[4:5]
	v_mov_b32_e32 v8, 0
	v_add_f32_e32 v6, v6, v7
	v_add_f32_e32 v16, v6, v9
	v_lshlrev_b32_e32 v7, 16, v120
	v_lshlrev_b32_e32 v6, 16, v116
	v_pk_mul_f32 v[6:7], v[6:7], v[4:5]
	v_mov_b32_e32 v9, 0
	v_add_f32_e32 v6, v6, v7
	v_add_f32_e32 v14, v6, v14
	v_and_b32_e32 v7, 0xffff0000, v120
	v_and_b32_e32 v6, 0xffff0000, v116
	v_pk_mul_f32 v[6:7], v[6:7], v[4:5]
	v_cvt_pk_fp8_f32 v8, v12, v15
	v_add_f32_e32 v6, v6, v7
	v_add_f32_e32 v10, v6, v10
	v_lshlrev_b32_e32 v7, 16, v121
	v_lshlrev_b32_e32 v6, 16, v117
	v_pk_mul_f32 v[6:7], v[6:7], v[4:5]
	v_cvt_pk_fp8_f32 v9, v14, v10
	v_add_f32_e32 v6, v6, v7
	v_lshlrev_b32_e32 v7, 16, v11
	v_add_f32_e32 v17, v6, v7
	v_and_b32_e32 v7, 0xffff0000, v121
	v_and_b32_e32 v6, 0xffff0000, v117
	v_pk_mul_f32 v[4:5], v[6:7], v[4:5]
	v_cvt_pk_fp8_f32 v8, v13, v16 op_sel:[0,0,1]
	v_add_f32_e32 v4, v4, v5
	v_and_b32_e32 v5, 0xffff0000, v11
	v_add_f32_e32 v4, v4, v5
	v_cvt_pk_fp8_f32 v9, v17, v4 op_sel:[0,0,1]
	v_mad_i64_i32 v[4:5], s[4:5], v186, s97, v[2:3]
	v_lshl_add_u64 v[10:11], v[4:5], 0, v[172:173]
	ds_read_b128 v[4:7], v242 offset:8192
	ds_bpermute_b32 v12, v252, v0
	ds_bpermute_b32 v13, v252, v178
	global_store_dwordx2 v[10:11], v[8:9], off
	ds_read_b128 v[8:11], v243 offset:8192
	s_waitcnt lgkmcnt(3)
	v_lshlrev_b32_e32 v14, 16, v4
	v_and_b32_e32 v15, 0xffff0000, v4
	v_lshlrev_b32_e32 v16, 16, v5
	v_and_b32_e32 v17, 0xffff0000, v5
	s_waitcnt vmcnt(8)
	v_lshlrev_b32_e32 v5, 16, v78
	v_lshlrev_b32_e32 v4, 16, v74
	s_waitcnt lgkmcnt(1)
	v_pk_mul_f32 v[4:5], v[4:5], v[12:13]
	v_lshlrev_b32_e32 v18, 16, v6
	v_add_f32_e32 v4, v4, v5
	v_add_f32_e32 v14, v4, v14
	v_and_b32_e32 v5, 0xffff0000, v78
	v_and_b32_e32 v4, 0xffff0000, v74
	v_pk_mul_f32 v[4:5], v[4:5], v[12:13]
	v_and_b32_e32 v6, 0xffff0000, v6
	v_add_f32_e32 v4, v4, v5
	v_add_f32_e32 v15, v4, v15
	v_lshlrev_b32_e32 v5, 16, v79
	v_lshlrev_b32_e32 v4, 16, v75
	v_pk_mul_f32 v[4:5], v[4:5], v[12:13]
	s_nop 0
	v_add_f32_e32 v4, v4, v5
	v_add_f32_e32 v16, v4, v16
	v_and_b32_e32 v5, 0xffff0000, v79
	v_and_b32_e32 v4, 0xffff0000, v75
	v_pk_mul_f32 v[4:5], v[4:5], v[12:13]
	s_nop 0
	v_add_f32_e32 v4, v4, v5
	v_add_f32_e32 v17, v4, v17
	v_lshlrev_b32_e32 v5, 16, v80
	v_lshlrev_b32_e32 v4, 16, v76
	v_pk_mul_f32 v[4:5], v[4:5], v[12:13]
	s_nop 0
	v_add_f32_e32 v4, v4, v5
	v_add_f32_e32 v18, v4, v18
	v_and_b32_e32 v5, 0xffff0000, v80
	v_and_b32_e32 v4, 0xffff0000, v76
	v_pk_mul_f32 v[4:5], v[4:5], v[12:13]
	s_nop 0
	v_add_f32_e32 v4, v4, v5
	v_add_f32_e32 v6, v4, v6
	v_lshlrev_b32_e32 v5, 16, v81
	v_lshlrev_b32_e32 v4, 16, v77
	v_pk_mul_f32 v[4:5], v[4:5], v[12:13]
	s_nop 0
	v_add_f32_e32 v4, v4, v5
	v_lshlrev_b32_e32 v5, 16, v7
	v_add_f32_e32 v19, v4, v5
	v_and_b32_e32 v5, 0xffff0000, v81
	v_and_b32_e32 v4, 0xffff0000, v77
	v_pk_mul_f32 v[4:5], v[4:5], v[12:13]
	s_waitcnt lgkmcnt(0)
	v_lshlrev_b32_e32 v13, 16, v10
	v_add_f32_e32 v12, v4, v5
	v_mov_b32_e32 v4, 0
	v_mov_b32_e32 v5, 0
	v_cvt_pk_fp8_f32 v4, v14, v15
	v_cvt_pk_fp8_f32 v5, v18, v6
	v_and_b32_e32 v6, 0xffff0000, v7
	v_add_f32_e32 v6, v12, v6
	v_cvt_pk_fp8_f32 v4, v16, v17 op_sel:[0,0,1]
	v_cvt_pk_fp8_f32 v5, v19, v6 op_sel:[0,0,1]
	v_mad_i64_i32 v[6:7], s[4:5], v184, s97, v[2:3]
	v_lshl_add_u64 v[6:7], v[6:7], 0, v[174:175]
	global_store_dwordx2 v[6:7], v[4:5], off
	ds_bpermute_b32 v4, v253, v0
	ds_bpermute_b32 v5, v253, v178
	s_waitcnt vmcnt(7)
	v_lshlrev_b32_e32 v7, 16, v70
	v_lshlrev_b32_e32 v6, 16, v66
	v_lshlrev_b32_e32 v0, 16, v8
	v_and_b32_e32 v8, 0xffff0000, v8
	s_waitcnt lgkmcnt(0)
	v_pk_mul_f32 v[6:7], v[6:7], v[4:5]
	v_lshlrev_b32_e32 v12, 16, v9
	v_add_f32_e32 v6, v6, v7
	v_add_f32_e32 v0, v6, v0
	v_and_b32_e32 v7, 0xffff0000, v70
	v_and_b32_e32 v6, 0xffff0000, v66
	v_pk_mul_f32 v[6:7], v[6:7], v[4:5]
	v_and_b32_e32 v9, 0xffff0000, v9
	v_add_f32_e32 v6, v6, v7
	v_add_f32_e32 v8, v6, v8
	v_lshlrev_b32_e32 v7, 16, v71
	v_lshlrev_b32_e32 v6, 16, v67
	v_pk_mul_f32 v[6:7], v[6:7], v[4:5]
	v_and_b32_e32 v10, 0xffff0000, v10
	v_add_f32_e32 v6, v6, v7
	v_add_f32_e32 v12, v6, v12
	v_and_b32_e32 v7, 0xffff0000, v71
	v_and_b32_e32 v6, 0xffff0000, v67
	v_pk_mul_f32 v[6:7], v[6:7], v[4:5]
	v_mad_i64_i32 v[2:3], s[4:5], v182, s97, v[2:3]
	v_add_f32_e32 v6, v6, v7
	v_add_f32_e32 v9, v6, v9
	v_lshlrev_b32_e32 v7, 16, v72
	v_lshlrev_b32_e32 v6, 16, v68
	v_pk_mul_f32 v[6:7], v[6:7], v[4:5]
	v_lshl_add_u64 v[2:3], v[2:3], 0, v[176:177]
	v_add_f32_e32 v6, v6, v7
	v_add_f32_e32 v13, v6, v13
	v_and_b32_e32 v7, 0xffff0000, v72
	v_and_b32_e32 v6, 0xffff0000, v68
	v_pk_mul_f32 v[6:7], v[6:7], v[4:5]
	s_nop 0
	v_add_f32_e32 v6, v6, v7
	v_add_f32_e32 v10, v6, v10
	v_lshlrev_b32_e32 v7, 16, v73
	v_lshlrev_b32_e32 v6, 16, v69
	v_pk_mul_f32 v[6:7], v[6:7], v[4:5]
	s_nop 0
	v_add_f32_e32 v6, v6, v7
	v_lshlrev_b32_e32 v7, 16, v11
	v_add_f32_e32 v14, v6, v7
	v_and_b32_e32 v7, 0xffff0000, v73
	v_and_b32_e32 v6, 0xffff0000, v69
	v_pk_mul_f32 v[4:5], v[6:7], v[4:5]
	s_nop 0
	v_add_f32_e32 v6, v4, v5
	v_mov_b32_e32 v4, 0
	v_mov_b32_e32 v5, 0
	v_cvt_pk_fp8_f32 v4, v0, v8
	v_cvt_pk_fp8_f32 v5, v13, v10
	v_and_b32_e32 v0, 0xffff0000, v11
	v_add_f32_e32 v0, v6, v0
	v_cvt_pk_fp8_f32 v4, v12, v9 op_sel:[0,0,1]
	v_cvt_pk_fp8_f32 v5, v14, v0 op_sel:[0,0,1]
	global_store_dwordx2 v[2:3], v[4:5], off
	s_waitcnt lgkmcnt(0)
	s_andn2_b64 vcc, exec, s[46:47]
	s_mov_b64 s[4:5], -1
	s_cbranch_vccnz .LBB0_473
; #define GAS __attribute__((address_space(1)))
; #define LAS __attribute__((address_space(3)))
; __device__ __forceinline__ void at_dma_v(LAS unsigned char* vdst, const bf16_t* vbase, int tq0, int dil, int tile, int lane_) { at_dma_k(vdst, vbase, tq0, dil, tile, lane_); }
; __device__ __forceinline__ void at_dma_k(LAS unsigned char* kdst, const bf16_t* kbase, int tq0, int dil, int tile, int lane_) {
;     int lane = lane_; asm volatile("" : "+v"(lane));
;     const int r0 = lane >> 3; const unsigned c0 = (unsigned)(((lane & 7) ^ r0) << 4);
;     const int t0 = tq0 + dil * (32 * tile + r0 - 64), d8 = 8 * dil;
; #pragma unroll
;     for (int n = 0; n < 4; ++n) { int tkn = t0 + n * d8; tkn = tkn < 0 ? 0 : (tkn > SEQ - 1 ? SEQ - 1 : tkn);
;         const unsigned off = ((unsigned)tkn << 7) + c0;
;         __builtin_amdgcn_global_load_lds((const unsigned*)((const GAS char*)kbase + off), (LAS unsigned*)(kdst + n * 1024), 16, 0, 0); }
; __device__ __forceinline__ void attn_unit(const bool FINAL, const bool HN, LAS unsigned char* wl, const bf16_t* qb, const bf16_t* kb, const bf16_t* vb, int tq0, int dil, float sl, bf16x8 (&qr)[8], const bf16_t* nqb, const bf16_t* nkb, const bf16_t* nvb, int ntq0, int ndil, ...
;     ...
;     if (HN) at_dma_v(vbuf, nvb, ntq0, ndil, 0, lane);
; }
	v_mov_b32_e32 v0, v198
	s_sub_i32 s4, s14, 64
	v_ashrrev_i32_e32 v2, 3, v0
	v_bitop3_b32 v0, v0, v2, 7 bitop3:0x6c
	v_add_u32_e32 v3, s4, v2
	v_lshlrev_b32_e32 v0, 4, v0
	v_med3_i32 v3, v3, 0, v244
	s_mov_b32 m0, s39
	v_lshl_add_u32 v3, v3, 7, v0
	s_sub_i32 s4, s14, 56
	global_load_lds_dwordx4 v3, s[30:31]
	v_add_u32_e32 v3, s4, v2
	v_med3_i32 v3, v3, 0, v244
	v_lshl_add_u32 v3, v3, 7, v0
	s_mov_b32 m0, s67
	s_sub_i32 s4, s14, 48
	global_load_lds_dwordx4 v3, s[30:31]
	v_add_u32_e32 v3, s4, v2
	s_sub_i32 s4, s14, 40
	v_med3_i32 v3, v3, 0, v244
	v_add_u32_e32 v2, s4, v2
	v_lshl_add_u32 v3, v3, 7, v0
	s_mov_b32 m0, s82
	v_med3_i32 v2, v2, 0, v244
	global_load_lds_dwordx4 v3, s[30:31]
	v_lshl_add_u32 v0, v2, 7, v0
	s_mov_b32 m0, s66
	s_mov_b64 s[4:5], 0
	global_load_lds_dwordx4 v0, s[30:31]
	s_branch .LBB0_473
